# P8 K-loop: hipcc accumulator renaming through temp v[82:85] removed (in-place accumulate, k-half-major order, no back-to-back dependent MFMA pairs); bit-identical; on top of v55
# speedup vs baseline: 1.0025x; 1.0025x over previous
;     __host__ __device__ bool next(int i, Unit& u) const { return at((long)i * G + c, u); }
; #define PG8_STAGE(bufoff, gbase, voff) do { _Pragma("unroll") for (int _i = 0; _i < 2; ++_i) \
;         __builtin_amdgcn_global_load_lds((const unsigned*)((const char*)(gbase) + (voff)[_i]), (PG8_LAS unsigned*)(lds + (bufoff) + ldsw + _i * 8192), 16, 0, 0); } while (0)
; #define PG8_BAR __builtin_amdgcn_s_barrier()
; template <class Epi, class Sched, bool ALIGN_EPI = false, bool SP2 = false>
; __device__ __forceinline__ void gemm_phase(PG8_LAS unsigned char* lds, const Gemm g, const Sched& S, const Epi& E) {
;     ...
;         const bool has_next = S.next(ui + 1, nxt);
;         const char* nA = has_next ? (const char*)g.A + (size_t)nxt.pm * tstep + (size_t)nxt.k0 * kstep : cA; const char* nB = has_next ? (const char*)g.Bt + (size_t)nxt.pn * tstep + (size_t)nxt.k0 * kstep : cB;
;         const int nt = cur.nt;
;         for (int t = 0; t < nt; t += 2) {
;             const bool last = (t == nt - 2);
;             const char* a1 = cA + (size_t)(t + 1) * kstep;
;             const char* a2 = last ? nA : cA + (size_t)(t + 2) * kstep; const char* b2 = last ? nB : cB + (size_t)(t + 2) * kstep;
;             const char* a3 = a2 + kstep; const char* b3 = b2 + kstep;
;             if (last && has_next) S.a_ready(nxt);
;             if constexpr (SP2) {
;             PG8_LDB(B0, 0, 0); PG8_LDB(B1, 0, 1); PG8_SCHED; PG8_LDA(At, 0, 0); PG8_STAGE(PG8_SA(1, 1), a1 + hstep, voffA);
;             PG8_WAIT_V(8); PG8_WAIT_L(0); PG8_BAR; PG8_MMA(0, 0, At, B0); PG8_MMA(0, 1, At, B1); PG8_BAR; PG8_SCHED;
;             PG8_LDA(At, 0, 1); PG8_STAGE(PG8_SB(0, 0), b2, voffB); PG8_STAGE(PG8_SB(0, 1), b2 + hstep, voffB); PG8_STAGE(PG8_SA(0, 0), a2, voffA);
;             PG8_WAIT_V(8); PG8_WAIT_L(0); PG8_BAR; PG8_MMA(1, 0, At, B0); PG8_MMA(1, 1, At, B1); PG8_BAR; PG8_SCHED;
;             PG8_LDB(B0, 1, 0); PG8_LDB(B1, 1, 1); PG8_SCHED; PG8_LDA(At, 1, 0); PG8_STAGE(PG8_SA(0, 1), a2 + hstep, voffA);
;             PG8_WAIT_V(8); PG8_WAIT_L(0); PG8_BAR; PG8_MMA(0, 0, At, B0); PG8_MMA(0, 1, At, B1); PG8_BAR; PG8_SCHED;
;             PG8_LDA(At, 1, 1); PG8_STAGE(PG8_SB(1, 0), b3, voffB); PG8_STAGE(PG8_SB(1, 1), b3 + hstep, voffB); PG8_STAGE(PG8_SA(1, 0), a3, voffA);
;             PG8_WAIT_V(8); PG8_WAIT_L(0); PG8_BAR; PG8_MMA(1, 0, At, B0); PG8_MMA(1, 1, At, B1); PG8_BAR; PG8_SCHED;
.LBB0_709:
	s_ashr_i32 s63, s62, 31
	s_lshl_b64 s[16:17], s[62:63], 21
	s_add_u32 s28, s4, s16
	s_addc_u32 s29, s5, s17
	s_and_b64 s[16:17], s[20:21], exec
	s_cselect_b32 s30, s29, s23
	s_cselect_b32 s31, s28, s22
	s_ashr_i32 s61, s60, 31
	s_lshl_b64 s[16:17], s[60:61], 21
	s_add_u32 s26, s6, s16
	s_addc_u32 s27, s7, s17
	s_and_b64 s[16:17], s[20:21], exec
	s_cselect_b32 s61, s27, s25
	s_cselect_b32 s63, s26, s24
	s_add_u32 s16, s24, 0x100
	s_addc_u32 s17, s25, 0
	s_add_u32 vcc_lo, s22, 0x100080
	s_addc_u32 vcc_hi, s23, 0
	s_mov_b32 s65, -2
	s_waitcnt vmcnt(0)
	s_add_u32 s22, vcc_lo, 0xfff00080
	s_addc_u32 s23, vcc_hi, -1
	s_add_i32 s68, 0, 0x10000
	s_cmp_eq_u32 s65, 60
	s_cselect_b32 s25, s30, s23
	s_cselect_b32 s24, s31, s22
	s_cselect_b32 s23, s61, s17
	s_cselect_b32 s22, s63, s16
	s_add_i32 s70, 0, 0x14000
	v_add_u32_e32 v70, s68, v220
	v_add_u32_e32 v170, s70, v220
	ds_read_b128 v[50:53], v70
	ds_read_b128 v[54:57], v70 offset:1024
	ds_read_b128 v[66:69], v70 offset:2048
	ds_read_b128 v[70:73], v70 offset:3072
	ds_read_b128 v[74:77], v170
	ds_read_b128 v[86:89], v170 offset:1024
	ds_read_b128 v[154:157], v170 offset:2048
	ds_read_b128 v[188:191], v170 offset:3072
	v_lshl_add_u64 v[170:171], vcc, 0, v[186:187]
	s_add_i32 m0, s10, 0xc000
	ds_read_b128 v[192:195], v222
	ds_read_b128 v[196:199], v222 offset:1024
	ds_read_b128 v[200:203], v222 offset:2048
	ds_read_b128 v[204:207], v222 offset:3072
	ds_read_b128 v[224:227], v222 offset:4096
	ds_read_b128 v[228:231], v222 offset:5120
	ds_read_b128 v[232:235], v222 offset:6144
	ds_read_b128 v[236:239], v222 offset:7168
	global_load_lds_dwordx4 v[170:171], off
	v_lshl_add_u64 v[170:171], vcc, 0, v[184:185]
	s_add_i32 m0, s10, 0xe000
	s_nop 0
	global_load_lds_dwordx4 v[170:171], off
	s_waitcnt vmcnt(8)
	s_waitcnt lgkmcnt(0)
	s_setprio 1
	s_barrier
	v_mfma_f32_16x16x32_bf16 v[142:145], v[50:53], v[192:195], 0
	v_mfma_f32_16x16x32_bf16 v[130:133], v[66:69], v[192:195], 0
	v_mfma_f32_16x16x32_bf16 v[138:141], v[50:53], v[200:203], 0
	v_mfma_f32_16x16x32_bf16 v[126:129], v[66:69], v[200:203], 0
	v_mfma_f32_16x16x32_bf16 v[118:121], v[50:53], v[224:227], 0
	v_mfma_f32_16x16x32_bf16 v[110:113], v[66:69], v[224:227], 0
	v_mfma_f32_16x16x32_bf16 v[98:101], v[50:53], v[232:235], 0
	v_mfma_f32_16x16x32_bf16 v[94:97], v[66:69], v[232:235], 0
	v_mfma_f32_16x16x32_bf16 v[142:145], v[54:57], v[196:199], v[142:145]
	v_mfma_f32_16x16x32_bf16 v[130:133], v[70:73], v[196:199], v[130:133]
	v_mfma_f32_16x16x32_bf16 v[138:141], v[54:57], v[204:207], v[138:141]
	v_mfma_f32_16x16x32_bf16 v[126:129], v[70:73], v[204:207], v[126:129]
	v_mfma_f32_16x16x32_bf16 v[118:121], v[54:57], v[228:231], v[118:121]
	v_mfma_f32_16x16x32_bf16 v[110:113], v[70:73], v[228:231], v[110:113]
	v_mfma_f32_16x16x32_bf16 v[98:101], v[54:57], v[236:239], v[98:101]
	v_mfma_f32_16x16x32_bf16 v[94:97], v[70:73], v[236:239], v[94:97]
	v_mfma_f32_16x16x32_bf16 v[150:153], v[74:77], v[192:195], 0
	v_mfma_f32_16x16x32_bf16 v[146:149], v[154:157], v[192:195], 0
	v_mfma_f32_16x16x32_bf16 v[134:137], v[74:77], v[200:203], 0
	v_mfma_f32_16x16x32_bf16 v[122:125], v[154:157], v[200:203], 0
	v_mfma_f32_16x16x32_bf16 v[114:117], v[74:77], v[224:227], 0
	v_mfma_f32_16x16x32_bf16 v[106:109], v[154:157], v[224:227], 0
	v_mfma_f32_16x16x32_bf16 v[102:105], v[74:77], v[232:235], 0
	v_mfma_f32_16x16x32_bf16 v[90:93], v[154:157], v[232:235], 0
	v_mfma_f32_16x16x32_bf16 v[150:153], v[86:89], v[196:199], v[150:153]
	v_mfma_f32_16x16x32_bf16 v[146:149], v[188:191], v[196:199], v[146:149]
	v_mfma_f32_16x16x32_bf16 v[134:137], v[86:89], v[204:207], v[134:137]
	v_mfma_f32_16x16x32_bf16 v[122:125], v[188:191], v[204:207], v[122:125]
	v_mfma_f32_16x16x32_bf16 v[114:117], v[86:89], v[228:231], v[114:117]
	v_mfma_f32_16x16x32_bf16 v[106:109], v[188:191], v[228:231], v[106:109]
	v_mfma_f32_16x16x32_bf16 v[102:105], v[86:89], v[236:239], v[102:105]
	v_mfma_f32_16x16x32_bf16 v[90:93], v[188:191], v[236:239], v[90:93]
	s_barrier
	s_setprio 0
	s_add_i32 s68, s68, s9
	v_lshl_add_u64 v[170:171], s[22:23], 0, v[158:159]
	s_mov_b32 m0, s68
	ds_read_b128 v[192:195], v222 offset:16384
	ds_read_b128 v[196:199], v222 offset:17408
	ds_read_b128 v[200:203], v222 offset:18432
	ds_read_b128 v[204:207], v222 offset:19456
	ds_read_b128 v[224:227], v222 offset:20480
	ds_read_b128 v[228:231], v222 offset:21504
	ds_read_b128 v[232:235], v222 offset:22528
	ds_read_b128 v[236:239], v222 offset:23552
	global_load_lds_dwordx4 v[170:171], off
	s_add_i32 m0, s68, 0x2000
	s_add_u32 s68, s22, 0x100000
	v_lshl_add_u64 v[208:209], s[22:23], 0, v[172:173]
	s_addc_u32 s69, s23, 0
	s_add_i32 s70, s70, s9
	global_load_lds_dwordx4 v[208:209], off
	v_lshl_add_u64 v[210:211], s[68:69], 0, v[158:159]
	s_mov_b32 m0, s70
	v_lshl_add_u64 v[244:245], s[24:25], 0, v[174:175]
	global_load_lds_dwordx4 v[210:211], off
	v_lshl_add_u64 v[210:211], s[68:69], 0, v[172:173]
	s_add_i32 m0, s70, 0x2000
	s_nop 0
	global_load_lds_dwordx4 v[210:211], off
	v_lshl_add_u64 v[210:211], s[24:25], 0, v[176:177]
	s_mov_b32 m0, s10
	s_nop 0
	global_load_lds_dwordx4 v[210:211], off
	s_mov_b32 m0, s11
	s_nop 0
	global_load_lds_dwordx4 v[244:245], off
	s_waitcnt vmcnt(8)
	s_waitcnt lgkmcnt(0)
	s_setprio 1
	s_barrier
; #define PG8_STAGE(bufoff, gbase, voff) do { _Pragma("unroll") for (int _i = 0; _i < 2; ++_i) \
;         __builtin_amdgcn_global_load_lds((const unsigned*)((const char*)(gbase) + (voff)[_i]), (PG8_LAS unsigned*)(lds + (bufoff) + ldsw + _i * 8192), 16, 0, 0); } while (0)
; #define PG8_LDA(dst, b, h) do { _Pragma("unroll") for (int m = 0; m < 4; ++m) _Pragma("unroll") for (int k = 0; k < 2; ++k) dst[m][k] = *(const PG8_LAS bf16x8*)(lds + PG8_SA(b, h) + aoff + m * 2048 + k * 1024); } while (0)
; #define PG8_LDB(dst, b, h) do { _Pragma("unroll") for (int n = 0; n < 2; ++n) _Pragma("unroll") for (int k = 0; k < 2; ++k) dst[n][k] = *(const PG8_LAS bf16x8*)(lds + PG8_SB(b, h) + boff + n * 2048 + k * 1024); } while (0)
; #define PG8_MMA(ai, bj, At, Bt) do { __builtin_amdgcn_s_setprio(1); _Pragma("unroll") for (int m = 0; m < 4; ++m) _Pragma("unroll") for (int n = 0; n < 2; ++n) _Pragma("unroll") for (int k = 0; k < 2; ++k) \
;         acc[ai][bj][m][n] = __builtin_amdgcn_mfma_f32_16x16x32_bf16(Bt[n][k], At[m][k], acc[ai][bj][m][n], 0, 0, 0); __builtin_amdgcn_s_setprio(0); } while (0)
; #define PG8_WAIT_V(n) asm volatile("s_waitcnt vmcnt(" #n ")" ::: "memory")
; #define PG8_WAIT_L(n) asm volatile("s_waitcnt lgkmcnt(" #n ")" ::: "memory")
; #define PG8_BAR __builtin_amdgcn_s_barrier()
; #define PG8_SCHED __builtin_amdgcn_sched_barrier(0)
; template <class Epi, class Sched, bool ALIGN_EPI = false, bool SP2 = false>
; __device__ __forceinline__ void gemm_phase(PG8_LAS unsigned char* lds, const Gemm g, const Sched& S, const Epi& E) {
;     ...
;             PG8_WAIT_V(8); PG8_WAIT_L(0); PG8_BAR; PG8_MMA(0, 0, At, B0); PG8_MMA(0, 1, At, B1); PG8_BAR; PG8_SCHED;
;             PG8_LDA(At, 0, 1); PG8_STAGE(PG8_SB(0, 0), b2, voffB); PG8_STAGE(PG8_SB(0, 1), b2 + hstep, voffB); PG8_STAGE(PG8_SA(0, 0), a2, voffA);
;             PG8_WAIT_V(8); PG8_WAIT_L(0); PG8_BAR; PG8_MMA(1, 0, At, B0); PG8_MMA(1, 1, At, B1); PG8_BAR; PG8_SCHED;
;             PG8_LDB(B0, 1, 0); PG8_LDB(B1, 1, 1); PG8_SCHED; PG8_LDA(At, 1, 0); PG8_STAGE(PG8_SA(0, 1), a2 + hstep, voffA);
;             PG8_WAIT_V(8); PG8_WAIT_L(0); PG8_BAR; PG8_MMA(0, 0, At, B0); PG8_MMA(0, 1, At, B1); PG8_BAR; PG8_SCHED;
	v_mfma_f32_16x16x32_bf16 v[62:65], v[50:53], v[192:195], 0
	v_mfma_f32_16x16x32_bf16 v[42:45], v[66:69], v[192:195], 0
	v_mfma_f32_16x16x32_bf16 v[58:61], v[50:53], v[200:203], 0
	v_mfma_f32_16x16x32_bf16 v[38:41], v[66:69], v[200:203], 0
	v_mfma_f32_16x16x32_bf16 v[30:33], v[50:53], v[224:227], 0
	v_mfma_f32_16x16x32_bf16 v[22:25], v[66:69], v[224:227], 0
	v_mfma_f32_16x16x32_bf16 v[10:13], v[50:53], v[232:235], 0
	v_mfma_f32_16x16x32_bf16 v[6:9], v[66:69], v[232:235], 0
	v_mfma_f32_16x16x32_bf16 v[62:65], v[54:57], v[196:199], v[62:65]
	v_mfma_f32_16x16x32_bf16 v[42:45], v[70:73], v[196:199], v[42:45]
	v_mfma_f32_16x16x32_bf16 v[58:61], v[54:57], v[204:207], v[58:61]
	v_mfma_f32_16x16x32_bf16 v[38:41], v[70:73], v[204:207], v[38:41]
	v_mfma_f32_16x16x32_bf16 v[30:33], v[54:57], v[228:231], v[30:33]
	v_mfma_f32_16x16x32_bf16 v[22:25], v[70:73], v[228:231], v[22:25]
	v_mfma_f32_16x16x32_bf16 v[10:13], v[54:57], v[236:239], v[10:13]
	v_mfma_f32_16x16x32_bf16 v[6:9], v[70:73], v[236:239], v[6:9]
	v_mfma_f32_16x16x32_bf16 v[46:49], v[74:77], v[200:203], 0
	v_mfma_f32_16x16x32_bf16 v[34:37], v[154:157], v[200:203], 0
	v_mfma_f32_16x16x32_bf16 v[26:29], v[74:77], v[224:227], 0
	v_mfma_f32_16x16x32_bf16 v[18:21], v[154:157], v[224:227], 0
	v_mfma_f32_16x16x32_bf16 v[14:17], v[74:77], v[232:235], 0
	v_mfma_f32_16x16x32_bf16 v[2:5], v[154:157], v[232:235], 0
	v_mfma_f32_16x16x32_bf16 v[50:53], v[74:77], v[192:195], 0
	v_mfma_f32_16x16x32_bf16 v[54:57], v[154:157], v[192:195], 0
	v_mfma_f32_16x16x32_bf16 v[46:49], v[86:89], v[204:207], v[46:49]
	v_mfma_f32_16x16x32_bf16 v[34:37], v[188:191], v[204:207], v[34:37]
	v_mfma_f32_16x16x32_bf16 v[26:29], v[86:89], v[228:231], v[26:29]
	v_mfma_f32_16x16x32_bf16 v[18:21], v[188:191], v[228:231], v[18:21]
	v_mfma_f32_16x16x32_bf16 v[14:17], v[86:89], v[236:239], v[14:17]
	v_mfma_f32_16x16x32_bf16 v[2:5], v[188:191], v[236:239], v[2:5]
	v_mfma_f32_16x16x32_bf16 v[50:53], v[86:89], v[196:199], v[50:53]
	v_mfma_f32_16x16x32_bf16 v[54:57], v[188:191], v[196:199], v[54:57]
	s_barrier
	s_setprio 0
	s_add_i32 s68, 0, 0x18000
	s_add_i32 s69, 0, 0x1c000
	v_add_u32_e32 v78, s68, v220
	v_add_u32_e32 v82, s69, v220
	ds_read_b128 v[66:69], v78
	ds_read_b128 v[70:73], v78 offset:1024
	ds_read_b128 v[74:77], v78 offset:2048
	ds_read_b128 v[78:81], v78 offset:3072
	ds_read_b128 v[86:89], v82
	ds_read_b128 v[154:157], v82 offset:1024
	ds_read_b128 v[188:191], v82 offset:2048
	ds_read_b128 v[192:195], v82 offset:3072
	s_add_u32 s24, s24, 0x100000
	s_addc_u32 s25, s25, 0
	s_mov_b32 m0, s12
	v_lshl_add_u64 v[240:241], s[24:25], 0, v[176:177]
	ds_read_b128 v[82:85], v222 offset:32768
	ds_read_b128 v[196:199], v222 offset:33792
	ds_read_b128 v[200:203], v222 offset:34816
	ds_read_b128 v[204:207], v222 offset:35840
	ds_read_b128 v[224:227], v222 offset:36864
	ds_read_b128 v[228:231], v222 offset:37888
	ds_read_b128 v[232:235], v222 offset:38912
	ds_read_b128 v[236:239], v222 offset:39936
	global_load_lds_dwordx4 v[240:241], off
	v_lshl_add_u64 v[240:241], s[24:25], 0, v[174:175]
	s_mov_b32 m0, s13
	s_nop 0
	global_load_lds_dwordx4 v[240:241], off
	s_waitcnt vmcnt(8)
	s_waitcnt lgkmcnt(0)
	s_setprio 1
	s_barrier
	v_mfma_f32_16x16x32_bf16 v[142:145], v[66:69], v[82:85], v[142:145]
	v_mfma_f32_16x16x32_bf16 v[130:133], v[74:77], v[82:85], v[130:133]
	v_mfma_f32_16x16x32_bf16 v[138:141], v[66:69], v[200:203], v[138:141]
	v_mfma_f32_16x16x32_bf16 v[126:129], v[74:77], v[200:203], v[126:129]
	v_mfma_f32_16x16x32_bf16 v[118:121], v[66:69], v[224:227], v[118:121]
	v_mfma_f32_16x16x32_bf16 v[110:113], v[74:77], v[224:227], v[110:113]
	v_mfma_f32_16x16x32_bf16 v[98:101], v[66:69], v[232:235], v[98:101]
	v_mfma_f32_16x16x32_bf16 v[94:97], v[74:77], v[232:235], v[94:97]
	v_mfma_f32_16x16x32_bf16 v[142:145], v[70:73], v[196:199], v[142:145]
	v_mfma_f32_16x16x32_bf16 v[130:133], v[78:81], v[196:199], v[130:133]
	v_mfma_f32_16x16x32_bf16 v[138:141], v[70:73], v[204:207], v[138:141]
	v_mfma_f32_16x16x32_bf16 v[126:129], v[78:81], v[204:207], v[126:129]
	v_mfma_f32_16x16x32_bf16 v[118:121], v[70:73], v[228:231], v[118:121]
	v_mfma_f32_16x16x32_bf16 v[110:113], v[78:81], v[228:231], v[110:113]
	v_mfma_f32_16x16x32_bf16 v[98:101], v[70:73], v[236:239], v[98:101]
	v_mfma_f32_16x16x32_bf16 v[94:97], v[78:81], v[236:239], v[94:97]
	v_mfma_f32_16x16x32_bf16 v[150:153], v[86:89], v[82:85], v[150:153]
	v_mfma_f32_16x16x32_bf16 v[146:149], v[188:191], v[82:85], v[146:149]
	v_mfma_f32_16x16x32_bf16 v[134:137], v[86:89], v[200:203], v[134:137]
	v_mfma_f32_16x16x32_bf16 v[122:125], v[188:191], v[200:203], v[122:125]
	v_mfma_f32_16x16x32_bf16 v[114:117], v[86:89], v[224:227], v[114:117]
	v_mfma_f32_16x16x32_bf16 v[106:109], v[188:191], v[224:227], v[106:109]
	v_mfma_f32_16x16x32_bf16 v[102:105], v[86:89], v[232:235], v[102:105]
	v_mfma_f32_16x16x32_bf16 v[90:93], v[188:191], v[232:235], v[90:93]
	v_mfma_f32_16x16x32_bf16 v[150:153], v[154:157], v[196:199], v[150:153]
	v_mfma_f32_16x16x32_bf16 v[146:149], v[192:195], v[196:199], v[146:149]
	v_mfma_f32_16x16x32_bf16 v[134:137], v[154:157], v[204:207], v[134:137]
	v_mfma_f32_16x16x32_bf16 v[122:125], v[192:195], v[204:207], v[122:125]
	v_mfma_f32_16x16x32_bf16 v[114:117], v[154:157], v[228:231], v[114:117]
	v_mfma_f32_16x16x32_bf16 v[106:109], v[192:195], v[228:231], v[106:109]
	v_mfma_f32_16x16x32_bf16 v[102:105], v[154:157], v[236:239], v[102:105]
	v_mfma_f32_16x16x32_bf16 v[90:93], v[192:195], v[236:239], v[90:93]
	s_barrier
; #define PG8_STAGE(bufoff, gbase, voff) do { _Pragma("unroll") for (int _i = 0; _i < 2; ++_i) \
;         __builtin_amdgcn_global_load_lds((const unsigned*)((const char*)(gbase) + (voff)[_i]), (PG8_LAS unsigned*)(lds + (bufoff) + ldsw + _i * 8192), 16, 0, 0); } while (0)
; #define PG8_LDA(dst, b, h) do { _Pragma("unroll") for (int m = 0; m < 4; ++m) _Pragma("unroll") for (int k = 0; k < 2; ++k) dst[m][k] = *(const PG8_LAS bf16x8*)(lds + PG8_SA(b, h) + aoff + m * 2048 + k * 1024); } while (0)
; #define PG8_MMA(ai, bj, At, Bt) do { __builtin_amdgcn_s_setprio(1); _Pragma("unroll") for (int m = 0; m < 4; ++m) _Pragma("unroll") for (int n = 0; n < 2; ++n) _Pragma("unroll") for (int k = 0; k < 2; ++k) \
;         acc[ai][bj][m][n] = __builtin_amdgcn_mfma_f32_16x16x32_bf16(Bt[n][k], At[m][k], acc[ai][bj][m][n], 0, 0, 0); __builtin_amdgcn_s_setprio(0); } while (0)
; #define PG8_WAIT_V(n) asm volatile("s_waitcnt vmcnt(" #n ")" ::: "memory")
; #define PG8_WAIT_L(n) asm volatile("s_waitcnt lgkmcnt(" #n ")" ::: "memory")
; #define PG8_BAR __builtin_amdgcn_s_barrier()
; #define PG8_SCHED __builtin_amdgcn_sched_barrier(0)
; template <class Epi, class Sched, bool ALIGN_EPI = false, bool SP2 = false>
; __device__ __forceinline__ void gemm_phase(PG8_LAS unsigned char* lds, const Gemm g, const Sched& S, const Epi& E) {
;     ...
;             PG8_WAIT_V(8); PG8_WAIT_L(0); PG8_BAR; PG8_MMA(0, 0, At, B0); PG8_MMA(0, 1, At, B1); PG8_BAR; PG8_SCHED;
;             PG8_LDA(At, 1, 1); PG8_STAGE(PG8_SB(1, 0), b3, voffB); PG8_STAGE(PG8_SB(1, 1), b3 + hstep, voffB); PG8_STAGE(PG8_SA(1, 0), a3, voffA);
;             PG8_WAIT_V(8); PG8_WAIT_L(0); PG8_BAR; PG8_MMA(1, 0, At, B0); PG8_MMA(1, 1, At, B1); PG8_BAR; PG8_SCHED;
	s_setprio 0
	s_add_i32 s24, s68, s9
	s_nop 2
	v_lshl_add_u64 v[82:83], v[170:171], 0, s[96:97]
	s_mov_b32 m0, s24
	ds_read_b128 v[196:199], v222 offset:49152
	ds_read_b128 v[200:203], v222 offset:50176
	ds_read_b128 v[204:207], v222 offset:51200
	ds_read_b128 v[224:227], v222 offset:52224
	ds_read_b128 v[228:231], v222 offset:53248
	ds_read_b128 v[232:235], v222 offset:54272
	ds_read_b128 v[236:239], v222 offset:55296
	ds_read_b128 v[240:243], v222 offset:56320
	global_load_lds_dwordx4 v[82:83], off
	s_add_i32 m0, s24, 0x2000
	s_add_u32 s22, s22, 0x100080
	v_lshl_add_u64 v[82:83], v[208:209], 0, s[96:97]
	s_addc_u32 s23, s23, 0
	s_add_i32 s24, s69, s9
	global_load_lds_dwordx4 v[82:83], off
	v_lshl_add_u64 v[82:83], s[22:23], 0, v[158:159]
	s_mov_b32 m0, s24
	s_nop 0
	global_load_lds_dwordx4 v[82:83], off
	v_lshl_add_u64 v[82:83], s[22:23], 0, v[172:173]
	s_add_i32 m0, s24, 0x2000
	s_nop 0
	global_load_lds_dwordx4 v[82:83], off
	v_lshl_add_u64 v[82:83], v[210:211], 0, s[96:97]
	s_mov_b32 m0, s0
	s_nop 0
	global_load_lds_dwordx4 v[82:83], off
	v_lshl_add_u64 v[82:83], v[244:245], 0, s[96:97]
	s_mov_b32 m0, s34
	s_nop 0
	global_load_lds_dwordx4 v[82:83], off
	s_waitcnt vmcnt(8)
	s_waitcnt lgkmcnt(0)
	s_setprio 1
	s_barrier
	v_mfma_f32_16x16x32_bf16 v[62:65], v[66:69], v[196:199], v[62:65]
	v_mfma_f32_16x16x32_bf16 v[42:45], v[74:77], v[196:199], v[42:45]
	v_mfma_f32_16x16x32_bf16 v[58:61], v[66:69], v[204:207], v[58:61]
	v_mfma_f32_16x16x32_bf16 v[38:41], v[74:77], v[204:207], v[38:41]
	v_mfma_f32_16x16x32_bf16 v[30:33], v[66:69], v[228:231], v[30:33]
	v_mfma_f32_16x16x32_bf16 v[22:25], v[74:77], v[228:231], v[22:25]
	v_mfma_f32_16x16x32_bf16 v[10:13], v[66:69], v[236:239], v[10:13]
	v_mfma_f32_16x16x32_bf16 v[6:9], v[74:77], v[236:239], v[6:9]
	v_mfma_f32_16x16x32_bf16 v[62:65], v[70:73], v[200:203], v[62:65]
	v_mfma_f32_16x16x32_bf16 v[42:45], v[78:81], v[200:203], v[42:45]
	v_mfma_f32_16x16x32_bf16 v[58:61], v[70:73], v[224:227], v[58:61]
	v_mfma_f32_16x16x32_bf16 v[38:41], v[78:81], v[224:227], v[38:41]
	v_mfma_f32_16x16x32_bf16 v[30:33], v[70:73], v[232:235], v[30:33]
	v_mfma_f32_16x16x32_bf16 v[22:25], v[78:81], v[232:235], v[22:25]
	v_mfma_f32_16x16x32_bf16 v[10:13], v[70:73], v[240:243], v[10:13]
	v_mfma_f32_16x16x32_bf16 v[6:9], v[78:81], v[240:243], v[6:9]
	v_mfma_f32_16x16x32_bf16 v[50:53], v[86:89], v[196:199], v[50:53]
	v_mfma_f32_16x16x32_bf16 v[54:57], v[188:191], v[196:199], v[54:57]
	v_mfma_f32_16x16x32_bf16 v[46:49], v[86:89], v[204:207], v[46:49]
	v_mfma_f32_16x16x32_bf16 v[34:37], v[188:191], v[204:207], v[34:37]
	v_mfma_f32_16x16x32_bf16 v[26:29], v[86:89], v[228:231], v[26:29]
	v_mfma_f32_16x16x32_bf16 v[18:21], v[188:191], v[228:231], v[18:21]
	v_mfma_f32_16x16x32_bf16 v[14:17], v[86:89], v[236:239], v[14:17]
	v_mfma_f32_16x16x32_bf16 v[2:5], v[188:191], v[236:239], v[2:5]
	v_mfma_f32_16x16x32_bf16 v[82:85], v[154:157], v[200:203], v[50:53]
	v_mfma_f32_16x16x32_bf16 v[78:81], v[192:195], v[200:203], v[54:57]
	v_mfma_f32_16x16x32_bf16 v[46:49], v[154:157], v[224:227], v[46:49]
	v_mfma_f32_16x16x32_bf16 v[34:37], v[192:195], v[224:227], v[34:37]
	v_mfma_f32_16x16x32_bf16 v[26:29], v[154:157], v[232:235], v[26:29]
	v_mfma_f32_16x16x32_bf16 v[18:21], v[192:195], v[232:235], v[18:21]
	v_mfma_f32_16x16x32_bf16 v[14:17], v[154:157], v[240:243], v[14:17]
	v_mfma_f32_16x16x32_bf16 v[2:5], v[192:195], v[240:243], v[2:5]
	s_barrier
	s_setprio 0
	s_add_i32 s65, s65, 2
	s_add_u32 s16, s16, 0x100
	s_addc_u32 s17, s17, 0
	s_add_u32 vcc_lo, vcc_lo, 0x100
	s_addc_u32 vcc_hi, vcc_hi, 0
	s_cmp_gt_u32 s65, 61
	s_cbranch_scc1 .Lpeel_exit_3
.LBB0_710:
	s_add_u32 s22, vcc_lo, 0xfff00080
	s_addc_u32 s23, vcc_hi, -1
	s_add_i32 s68, 0, 0x10000
	s_cmp_eq_u32 s65, 60
	s_cselect_b32 s25, s30, s23
	s_cselect_b32 s24, s31, s22
	s_cselect_b32 s23, s61, s17
	s_cselect_b32 s22, s63, s16
	s_add_i32 s70, 0, 0x14000
	v_add_u32_e32 v70, s68, v220
	v_add_u32_e32 v170, s70, v220
	ds_read_b128 v[50:53], v70
	ds_read_b128 v[54:57], v70 offset:1024
	ds_read_b128 v[66:69], v70 offset:2048
	ds_read_b128 v[70:73], v70 offset:3072
	ds_read_b128 v[74:77], v170
	ds_read_b128 v[86:89], v170 offset:1024
	ds_read_b128 v[154:157], v170 offset:2048
	ds_read_b128 v[188:191], v170 offset:3072
	v_lshl_add_u64 v[170:171], vcc, 0, v[186:187]
	s_add_i32 m0, s10, 0xc000
	ds_read_b128 v[192:195], v222
	ds_read_b128 v[196:199], v222 offset:1024
	ds_read_b128 v[200:203], v222 offset:2048
	ds_read_b128 v[204:207], v222 offset:3072
	ds_read_b128 v[224:227], v222 offset:4096
	ds_read_b128 v[228:231], v222 offset:5120
	ds_read_b128 v[232:235], v222 offset:6144
	ds_read_b128 v[236:239], v222 offset:7168
	global_load_lds_dwordx4 v[170:171], off
	v_lshl_add_u64 v[170:171], vcc, 0, v[184:185]
	s_add_i32 m0, s10, 0xe000
	s_nop 0
	global_load_lds_dwordx4 v[170:171], off
	s_waitcnt vmcnt(8)
	s_waitcnt lgkmcnt(0)
	s_setprio 1
	s_barrier
; #define PG8_STAGE(bufoff, gbase, voff) do { _Pragma("unroll") for (int _i = 0; _i < 2; ++_i) \
;         __builtin_amdgcn_global_load_lds((const unsigned*)((const char*)(gbase) + (voff)[_i]), (PG8_LAS unsigned*)(lds + (bufoff) + ldsw + _i * 8192), 16, 0, 0); } while (0)
; #define PG8_LDA(dst, b, h) do { _Pragma("unroll") for (int m = 0; m < 4; ++m) _Pragma("unroll") for (int k = 0; k < 2; ++k) dst[m][k] = *(const PG8_LAS bf16x8*)(lds + PG8_SA(b, h) + aoff + m * 2048 + k * 1024); } while (0)
; #define PG8_LDB(dst, b, h) do { _Pragma("unroll") for (int n = 0; n < 2; ++n) _Pragma("unroll") for (int k = 0; k < 2; ++k) dst[n][k] = *(const PG8_LAS bf16x8*)(lds + PG8_SB(b, h) + boff + n * 2048 + k * 1024); } while (0)
; #define PG8_MMA(ai, bj, At, Bt) do { __builtin_amdgcn_s_setprio(1); _Pragma("unroll") for (int m = 0; m < 4; ++m) _Pragma("unroll") for (int n = 0; n < 2; ++n) _Pragma("unroll") for (int k = 0; k < 2; ++k) \
;         acc[ai][bj][m][n] = __builtin_amdgcn_mfma_f32_16x16x32_bf16(Bt[n][k], At[m][k], acc[ai][bj][m][n], 0, 0, 0); __builtin_amdgcn_s_setprio(0); } while (0)
; #define PG8_WAIT_V(n) asm volatile("s_waitcnt vmcnt(" #n ")" ::: "memory")
; #define PG8_WAIT_L(n) asm volatile("s_waitcnt lgkmcnt(" #n ")" ::: "memory")
; #define PG8_BAR __builtin_amdgcn_s_barrier()
; #define PG8_SCHED __builtin_amdgcn_sched_barrier(0)
; template <class Epi, class Sched, bool ALIGN_EPI = false, bool SP2 = false>
; __device__ __forceinline__ void gemm_phase(PG8_LAS unsigned char* lds, const Gemm g, const Sched& S, const Epi& E) {
;     ...
;             PG8_LDB(B0, 0, 0); PG8_LDB(B1, 0, 1); PG8_SCHED; PG8_LDA(At, 0, 0); PG8_STAGE(PG8_SA(1, 1), a1 + hstep, voffA);
;             PG8_WAIT_V(8); PG8_WAIT_L(0); PG8_BAR; PG8_MMA(0, 0, At, B0); PG8_MMA(0, 1, At, B1); PG8_BAR; PG8_SCHED;
;             PG8_LDA(At, 0, 1); PG8_STAGE(PG8_SB(0, 0), b2, voffB); PG8_STAGE(PG8_SB(0, 1), b2 + hstep, voffB); PG8_STAGE(PG8_SA(0, 0), a2, voffA);
;             PG8_WAIT_V(8); PG8_WAIT_L(0); PG8_BAR; PG8_MMA(1, 0, At, B0); PG8_MMA(1, 1, At, B1); PG8_BAR; PG8_SCHED;
	v_mfma_f32_16x16x32_bf16 v[142:145], v[50:53], v[192:195], v[142:145]
	v_mfma_f32_16x16x32_bf16 v[130:133], v[66:69], v[192:195], v[130:133]
	v_mfma_f32_16x16x32_bf16 v[138:141], v[50:53], v[200:203], v[138:141]
	v_mfma_f32_16x16x32_bf16 v[126:129], v[66:69], v[200:203], v[126:129]
	v_mfma_f32_16x16x32_bf16 v[118:121], v[50:53], v[224:227], v[118:121]
	v_mfma_f32_16x16x32_bf16 v[110:113], v[66:69], v[224:227], v[110:113]
	v_mfma_f32_16x16x32_bf16 v[98:101], v[50:53], v[232:235], v[98:101]
	v_mfma_f32_16x16x32_bf16 v[94:97], v[66:69], v[232:235], v[94:97]
	v_mfma_f32_16x16x32_bf16 v[142:145], v[54:57], v[196:199], v[142:145]
	v_mfma_f32_16x16x32_bf16 v[130:133], v[70:73], v[196:199], v[130:133]
	v_mfma_f32_16x16x32_bf16 v[138:141], v[54:57], v[204:207], v[138:141]
	v_mfma_f32_16x16x32_bf16 v[126:129], v[70:73], v[204:207], v[126:129]
	v_mfma_f32_16x16x32_bf16 v[118:121], v[54:57], v[228:231], v[118:121]
	v_mfma_f32_16x16x32_bf16 v[110:113], v[70:73], v[228:231], v[110:113]
	v_mfma_f32_16x16x32_bf16 v[98:101], v[54:57], v[236:239], v[98:101]
	v_mfma_f32_16x16x32_bf16 v[94:97], v[70:73], v[236:239], v[94:97]
	v_mfma_f32_16x16x32_bf16 v[150:153], v[74:77], v[192:195], v[150:153]
	v_mfma_f32_16x16x32_bf16 v[146:149], v[154:157], v[192:195], v[146:149]
	v_mfma_f32_16x16x32_bf16 v[134:137], v[74:77], v[200:203], v[134:137]
	v_mfma_f32_16x16x32_bf16 v[122:125], v[154:157], v[200:203], v[122:125]
	v_mfma_f32_16x16x32_bf16 v[114:117], v[74:77], v[224:227], v[114:117]
	v_mfma_f32_16x16x32_bf16 v[106:109], v[154:157], v[224:227], v[106:109]
	v_mfma_f32_16x16x32_bf16 v[102:105], v[74:77], v[232:235], v[102:105]
	v_mfma_f32_16x16x32_bf16 v[90:93], v[154:157], v[232:235], v[90:93]
	v_mfma_f32_16x16x32_bf16 v[150:153], v[86:89], v[196:199], v[150:153]
	v_mfma_f32_16x16x32_bf16 v[146:149], v[188:191], v[196:199], v[146:149]
	v_mfma_f32_16x16x32_bf16 v[134:137], v[86:89], v[204:207], v[134:137]
	v_mfma_f32_16x16x32_bf16 v[122:125], v[188:191], v[204:207], v[122:125]
	v_mfma_f32_16x16x32_bf16 v[114:117], v[86:89], v[228:231], v[114:117]
	v_mfma_f32_16x16x32_bf16 v[106:109], v[188:191], v[228:231], v[106:109]
	v_mfma_f32_16x16x32_bf16 v[102:105], v[86:89], v[236:239], v[102:105]
	v_mfma_f32_16x16x32_bf16 v[90:93], v[188:191], v[236:239], v[90:93]
	s_barrier
	s_setprio 0
	s_add_i32 s68, s68, s9
	v_lshl_add_u64 v[170:171], s[22:23], 0, v[158:159]
	s_mov_b32 m0, s68
	ds_read_b128 v[192:195], v222 offset:16384
	ds_read_b128 v[196:199], v222 offset:17408
	ds_read_b128 v[200:203], v222 offset:18432
	ds_read_b128 v[204:207], v222 offset:19456
	ds_read_b128 v[224:227], v222 offset:20480
	ds_read_b128 v[228:231], v222 offset:21504
	ds_read_b128 v[232:235], v222 offset:22528
	ds_read_b128 v[236:239], v222 offset:23552
	global_load_lds_dwordx4 v[170:171], off
	s_add_i32 m0, s68, 0x2000
	s_add_u32 s68, s22, 0x100000
	v_lshl_add_u64 v[208:209], s[22:23], 0, v[172:173]
	s_addc_u32 s69, s23, 0
	s_add_i32 s70, s70, s9
	global_load_lds_dwordx4 v[208:209], off
	v_lshl_add_u64 v[210:211], s[68:69], 0, v[158:159]
	s_mov_b32 m0, s70
	v_lshl_add_u64 v[244:245], s[24:25], 0, v[174:175]
	global_load_lds_dwordx4 v[210:211], off
	v_lshl_add_u64 v[210:211], s[68:69], 0, v[172:173]
	s_add_i32 m0, s70, 0x2000
	s_nop 0
	global_load_lds_dwordx4 v[210:211], off
	v_lshl_add_u64 v[210:211], s[24:25], 0, v[176:177]
	s_mov_b32 m0, s10
	s_nop 0
	global_load_lds_dwordx4 v[210:211], off
	s_mov_b32 m0, s11
	s_nop 0
	global_load_lds_dwordx4 v[244:245], off
	s_waitcnt vmcnt(8)
	s_waitcnt lgkmcnt(0)
	s_setprio 1
	s_barrier
	v_mfma_f32_16x16x32_bf16 v[62:65], v[50:53], v[192:195], v[62:65]
	v_mfma_f32_16x16x32_bf16 v[42:45], v[66:69], v[192:195], v[42:45]
	v_mfma_f32_16x16x32_bf16 v[58:61], v[50:53], v[200:203], v[58:61]
	v_mfma_f32_16x16x32_bf16 v[38:41], v[66:69], v[200:203], v[38:41]
	v_mfma_f32_16x16x32_bf16 v[30:33], v[50:53], v[224:227], v[30:33]
	v_mfma_f32_16x16x32_bf16 v[22:25], v[66:69], v[224:227], v[22:25]
	v_mfma_f32_16x16x32_bf16 v[10:13], v[50:53], v[232:235], v[10:13]
	v_mfma_f32_16x16x32_bf16 v[6:9], v[66:69], v[232:235], v[6:9]
	v_mfma_f32_16x16x32_bf16 v[62:65], v[54:57], v[196:199], v[62:65]
	v_mfma_f32_16x16x32_bf16 v[42:45], v[70:73], v[196:199], v[42:45]
	v_mfma_f32_16x16x32_bf16 v[58:61], v[54:57], v[204:207], v[58:61]
	v_mfma_f32_16x16x32_bf16 v[38:41], v[70:73], v[204:207], v[38:41]
	v_mfma_f32_16x16x32_bf16 v[30:33], v[54:57], v[228:231], v[30:33]
	v_mfma_f32_16x16x32_bf16 v[22:25], v[70:73], v[228:231], v[22:25]
	v_mfma_f32_16x16x32_bf16 v[10:13], v[54:57], v[236:239], v[10:13]
	v_mfma_f32_16x16x32_bf16 v[6:9], v[70:73], v[236:239], v[6:9]
	v_mfma_f32_16x16x32_bf16 v[46:49], v[74:77], v[200:203], v[46:49]
	v_mfma_f32_16x16x32_bf16 v[34:37], v[154:157], v[200:203], v[34:37]
	v_mfma_f32_16x16x32_bf16 v[26:29], v[74:77], v[224:227], v[26:29]
	v_mfma_f32_16x16x32_bf16 v[18:21], v[154:157], v[224:227], v[18:21]
	v_mfma_f32_16x16x32_bf16 v[14:17], v[74:77], v[232:235], v[14:17]
	v_mfma_f32_16x16x32_bf16 v[2:5], v[154:157], v[232:235], v[2:5]
	v_mfma_f32_16x16x32_bf16 v[50:53], v[74:77], v[192:195], v[82:85]
	v_mfma_f32_16x16x32_bf16 v[54:57], v[154:157], v[192:195], v[78:81]
	v_mfma_f32_16x16x32_bf16 v[46:49], v[86:89], v[204:207], v[46:49]
	v_mfma_f32_16x16x32_bf16 v[34:37], v[188:191], v[204:207], v[34:37]
	v_mfma_f32_16x16x32_bf16 v[26:29], v[86:89], v[228:231], v[26:29]
	v_mfma_f32_16x16x32_bf16 v[18:21], v[188:191], v[228:231], v[18:21]
	v_mfma_f32_16x16x32_bf16 v[14:17], v[86:89], v[236:239], v[14:17]
	v_mfma_f32_16x16x32_bf16 v[2:5], v[188:191], v[236:239], v[2:5]
	v_mfma_f32_16x16x32_bf16 v[50:53], v[86:89], v[196:199], v[50:53]
	v_mfma_f32_16x16x32_bf16 v[54:57], v[188:191], v[196:199], v[54:57]
	s_barrier
; #define PG8_STAGE(bufoff, gbase, voff) do { _Pragma("unroll") for (int _i = 0; _i < 2; ++_i) \
;         __builtin_amdgcn_global_load_lds((const unsigned*)((const char*)(gbase) + (voff)[_i]), (PG8_LAS unsigned*)(lds + (bufoff) + ldsw + _i * 8192), 16, 0, 0); } while (0)
; #define PG8_LDA(dst, b, h) do { _Pragma("unroll") for (int m = 0; m < 4; ++m) _Pragma("unroll") for (int k = 0; k < 2; ++k) dst[m][k] = *(const PG8_LAS bf16x8*)(lds + PG8_SA(b, h) + aoff + m * 2048 + k * 1024); } while (0)
; #define PG8_LDB(dst, b, h) do { _Pragma("unroll") for (int n = 0; n < 2; ++n) _Pragma("unroll") for (int k = 0; k < 2; ++k) dst[n][k] = *(const PG8_LAS bf16x8*)(lds + PG8_SB(b, h) + boff + n * 2048 + k * 1024); } while (0)
; #define PG8_MMA(ai, bj, At, Bt) do { __builtin_amdgcn_s_setprio(1); _Pragma("unroll") for (int m = 0; m < 4; ++m) _Pragma("unroll") for (int n = 0; n < 2; ++n) _Pragma("unroll") for (int k = 0; k < 2; ++k) \
;         acc[ai][bj][m][n] = __builtin_amdgcn_mfma_f32_16x16x32_bf16(Bt[n][k], At[m][k], acc[ai][bj][m][n], 0, 0, 0); __builtin_amdgcn_s_setprio(0); } while (0)
; #define PG8_WAIT_V(n) asm volatile("s_waitcnt vmcnt(" #n ")" ::: "memory")
; #define PG8_WAIT_L(n) asm volatile("s_waitcnt lgkmcnt(" #n ")" ::: "memory")
; #define PG8_BAR __builtin_amdgcn_s_barrier()
; #define PG8_SCHED __builtin_amdgcn_sched_barrier(0)
; template <class Epi, class Sched, bool ALIGN_EPI = false, bool SP2 = false>
; __device__ __forceinline__ void gemm_phase(PG8_LAS unsigned char* lds, const Gemm g, const Sched& S, const Epi& E) {
;     ...
;             PG8_LDB(B0, 1, 0); PG8_LDB(B1, 1, 1); PG8_SCHED; PG8_LDA(At, 1, 0); PG8_STAGE(PG8_SA(0, 1), a2 + hstep, voffA);
;             PG8_WAIT_V(8); PG8_WAIT_L(0); PG8_BAR; PG8_MMA(0, 0, At, B0); PG8_MMA(0, 1, At, B1); PG8_BAR; PG8_SCHED;
;             PG8_LDA(At, 1, 1); PG8_STAGE(PG8_SB(1, 0), b3, voffB); PG8_STAGE(PG8_SB(1, 1), b3 + hstep, voffB); PG8_STAGE(PG8_SA(1, 0), a3, voffA);
;             PG8_WAIT_V(8); PG8_WAIT_L(0); PG8_BAR; PG8_MMA(1, 0, At, B0); PG8_MMA(1, 1, At, B1); PG8_BAR; PG8_SCHED;
	s_setprio 0
	s_add_i32 s68, 0, 0x18000
	s_add_i32 s69, 0, 0x1c000
	v_add_u32_e32 v78, s68, v220
	v_add_u32_e32 v82, s69, v220
	ds_read_b128 v[66:69], v78
	ds_read_b128 v[70:73], v78 offset:1024
	ds_read_b128 v[74:77], v78 offset:2048
	ds_read_b128 v[78:81], v78 offset:3072
	ds_read_b128 v[86:89], v82
	ds_read_b128 v[154:157], v82 offset:1024
	ds_read_b128 v[188:191], v82 offset:2048
	ds_read_b128 v[192:195], v82 offset:3072
	s_add_u32 s24, s24, 0x100000
	s_addc_u32 s25, s25, 0
	s_mov_b32 m0, s12
	v_lshl_add_u64 v[240:241], s[24:25], 0, v[176:177]
	ds_read_b128 v[82:85], v222 offset:32768
	ds_read_b128 v[196:199], v222 offset:33792
	ds_read_b128 v[200:203], v222 offset:34816
	ds_read_b128 v[204:207], v222 offset:35840
	ds_read_b128 v[224:227], v222 offset:36864
	ds_read_b128 v[228:231], v222 offset:37888
	ds_read_b128 v[232:235], v222 offset:38912
	ds_read_b128 v[236:239], v222 offset:39936
	global_load_lds_dwordx4 v[240:241], off
	v_lshl_add_u64 v[240:241], s[24:25], 0, v[174:175]
	s_mov_b32 m0, s13
	s_nop 0
	global_load_lds_dwordx4 v[240:241], off
	s_waitcnt vmcnt(8)
	s_waitcnt lgkmcnt(0)
	s_setprio 1
	s_barrier
	v_mfma_f32_16x16x32_bf16 v[142:145], v[66:69], v[82:85], v[142:145]
	v_mfma_f32_16x16x32_bf16 v[130:133], v[74:77], v[82:85], v[130:133]
	v_mfma_f32_16x16x32_bf16 v[138:141], v[66:69], v[200:203], v[138:141]
	v_mfma_f32_16x16x32_bf16 v[126:129], v[74:77], v[200:203], v[126:129]
	v_mfma_f32_16x16x32_bf16 v[118:121], v[66:69], v[224:227], v[118:121]
	v_mfma_f32_16x16x32_bf16 v[110:113], v[74:77], v[224:227], v[110:113]
	v_mfma_f32_16x16x32_bf16 v[98:101], v[66:69], v[232:235], v[98:101]
	v_mfma_f32_16x16x32_bf16 v[94:97], v[74:77], v[232:235], v[94:97]
	v_mfma_f32_16x16x32_bf16 v[142:145], v[70:73], v[196:199], v[142:145]
	v_mfma_f32_16x16x32_bf16 v[130:133], v[78:81], v[196:199], v[130:133]
	v_mfma_f32_16x16x32_bf16 v[138:141], v[70:73], v[204:207], v[138:141]
	v_mfma_f32_16x16x32_bf16 v[126:129], v[78:81], v[204:207], v[126:129]
	v_mfma_f32_16x16x32_bf16 v[118:121], v[70:73], v[228:231], v[118:121]
	v_mfma_f32_16x16x32_bf16 v[110:113], v[78:81], v[228:231], v[110:113]
	v_mfma_f32_16x16x32_bf16 v[98:101], v[70:73], v[236:239], v[98:101]
	v_mfma_f32_16x16x32_bf16 v[94:97], v[78:81], v[236:239], v[94:97]
	v_mfma_f32_16x16x32_bf16 v[150:153], v[86:89], v[82:85], v[150:153]
	v_mfma_f32_16x16x32_bf16 v[146:149], v[188:191], v[82:85], v[146:149]
	v_mfma_f32_16x16x32_bf16 v[134:137], v[86:89], v[200:203], v[134:137]
	v_mfma_f32_16x16x32_bf16 v[122:125], v[188:191], v[200:203], v[122:125]
	v_mfma_f32_16x16x32_bf16 v[114:117], v[86:89], v[224:227], v[114:117]
	v_mfma_f32_16x16x32_bf16 v[106:109], v[188:191], v[224:227], v[106:109]
	v_mfma_f32_16x16x32_bf16 v[102:105], v[86:89], v[232:235], v[102:105]
	v_mfma_f32_16x16x32_bf16 v[90:93], v[188:191], v[232:235], v[90:93]
	v_mfma_f32_16x16x32_bf16 v[150:153], v[154:157], v[196:199], v[150:153]
	v_mfma_f32_16x16x32_bf16 v[146:149], v[192:195], v[196:199], v[146:149]
	v_mfma_f32_16x16x32_bf16 v[134:137], v[154:157], v[204:207], v[134:137]
	v_mfma_f32_16x16x32_bf16 v[122:125], v[192:195], v[204:207], v[122:125]
	v_mfma_f32_16x16x32_bf16 v[114:117], v[154:157], v[228:231], v[114:117]
	v_mfma_f32_16x16x32_bf16 v[106:109], v[192:195], v[228:231], v[106:109]
	v_mfma_f32_16x16x32_bf16 v[102:105], v[154:157], v[236:239], v[102:105]
	v_mfma_f32_16x16x32_bf16 v[90:93], v[192:195], v[236:239], v[90:93]
	s_barrier
	s_setprio 0
	s_add_i32 s24, s68, s9
	s_nop 2
	v_lshl_add_u64 v[82:83], v[170:171], 0, s[96:97]
	s_mov_b32 m0, s24
	ds_read_b128 v[196:199], v222 offset:49152
	ds_read_b128 v[200:203], v222 offset:50176
	ds_read_b128 v[204:207], v222 offset:51200
	ds_read_b128 v[224:227], v222 offset:52224
	ds_read_b128 v[228:231], v222 offset:53248
	ds_read_b128 v[232:235], v222 offset:54272
	ds_read_b128 v[236:239], v222 offset:55296
	ds_read_b128 v[240:243], v222 offset:56320
	global_load_lds_dwordx4 v[82:83], off
	s_add_i32 m0, s24, 0x2000
	s_add_u32 s22, s22, 0x100080
	v_lshl_add_u64 v[82:83], v[208:209], 0, s[96:97]
	s_addc_u32 s23, s23, 0
	s_add_i32 s24, s69, s9
	global_load_lds_dwordx4 v[82:83], off
	v_lshl_add_u64 v[82:83], s[22:23], 0, v[158:159]
	s_mov_b32 m0, s24
	s_nop 0
	global_load_lds_dwordx4 v[82:83], off
	v_lshl_add_u64 v[82:83], s[22:23], 0, v[172:173]
	s_add_i32 m0, s24, 0x2000
	s_nop 0
	global_load_lds_dwordx4 v[82:83], off
	v_lshl_add_u64 v[82:83], v[210:211], 0, s[96:97]
	s_mov_b32 m0, s0
	s_nop 0
	global_load_lds_dwordx4 v[82:83], off
	v_lshl_add_u64 v[82:83], v[244:245], 0, s[96:97]
	s_mov_b32 m0, s34
	s_nop 0
	global_load_lds_dwordx4 v[82:83], off
	s_waitcnt vmcnt(8)
	s_waitcnt lgkmcnt(0)
	s_setprio 1
	s_barrier
	v_mfma_f32_16x16x32_bf16 v[62:65], v[66:69], v[196:199], v[62:65]
	v_mfma_f32_16x16x32_bf16 v[42:45], v[74:77], v[196:199], v[42:45]
	v_mfma_f32_16x16x32_bf16 v[58:61], v[66:69], v[204:207], v[58:61]
	v_mfma_f32_16x16x32_bf16 v[38:41], v[74:77], v[204:207], v[38:41]
	v_mfma_f32_16x16x32_bf16 v[30:33], v[66:69], v[228:231], v[30:33]
	v_mfma_f32_16x16x32_bf16 v[22:25], v[74:77], v[228:231], v[22:25]
	v_mfma_f32_16x16x32_bf16 v[10:13], v[66:69], v[236:239], v[10:13]
	v_mfma_f32_16x16x32_bf16 v[6:9], v[74:77], v[236:239], v[6:9]
	v_mfma_f32_16x16x32_bf16 v[62:65], v[70:73], v[200:203], v[62:65]
	v_mfma_f32_16x16x32_bf16 v[42:45], v[78:81], v[200:203], v[42:45]
	v_mfma_f32_16x16x32_bf16 v[58:61], v[70:73], v[224:227], v[58:61]
	v_mfma_f32_16x16x32_bf16 v[38:41], v[78:81], v[224:227], v[38:41]
	v_mfma_f32_16x16x32_bf16 v[30:33], v[70:73], v[232:235], v[30:33]
	v_mfma_f32_16x16x32_bf16 v[22:25], v[78:81], v[232:235], v[22:25]
	v_mfma_f32_16x16x32_bf16 v[10:13], v[70:73], v[240:243], v[10:13]
	v_mfma_f32_16x16x32_bf16 v[6:9], v[78:81], v[240:243], v[6:9]
	v_mfma_f32_16x16x32_bf16 v[50:53], v[86:89], v[196:199], v[50:53]
	v_mfma_f32_16x16x32_bf16 v[54:57], v[188:191], v[196:199], v[54:57]
	v_mfma_f32_16x16x32_bf16 v[46:49], v[86:89], v[204:207], v[46:49]
	v_mfma_f32_16x16x32_bf16 v[34:37], v[188:191], v[204:207], v[34:37]
	v_mfma_f32_16x16x32_bf16 v[26:29], v[86:89], v[228:231], v[26:29]
	v_mfma_f32_16x16x32_bf16 v[18:21], v[188:191], v[228:231], v[18:21]
	v_mfma_f32_16x16x32_bf16 v[14:17], v[86:89], v[236:239], v[14:17]
	v_mfma_f32_16x16x32_bf16 v[2:5], v[188:191], v[236:239], v[2:5]
	v_mfma_f32_16x16x32_bf16 v[82:85], v[154:157], v[200:203], v[50:53]
	v_mfma_f32_16x16x32_bf16 v[78:81], v[192:195], v[200:203], v[54:57]
	v_mfma_f32_16x16x32_bf16 v[46:49], v[154:157], v[224:227], v[46:49]
	v_mfma_f32_16x16x32_bf16 v[34:37], v[192:195], v[224:227], v[34:37]
	v_mfma_f32_16x16x32_bf16 v[26:29], v[154:157], v[232:235], v[26:29]
	v_mfma_f32_16x16x32_bf16 v[18:21], v[192:195], v[232:235], v[18:21]
	v_mfma_f32_16x16x32_bf16 v[14:17], v[154:157], v[240:243], v[14:17]
	v_mfma_f32_16x16x32_bf16 v[2:5], v[192:195], v[240:243], v[2:5]
	s_barrier
	s_setprio 0
	s_add_i32 s65, s65, 2
	s_add_u32 s16, s16, 0x100
	s_addc_u32 s17, s17, 0
	s_add_u32 vcc_lo, vcc_lo, 0x100
	s_addc_u32 vcc_hi, vcc_hi, 0
	s_cmp_gt_u32 s65, 61
	s_cbranch_scc0 .LBB0_710
